# gates stored as 1+exp(-x) in bf16 (same width), reciprocal deferred to the merge seams/final scale: 25% fewer transcendental ops across P2.5+P3
# speedup vs baseline: 1.0088x; 1.0025x over previous
.LBB0_540:
	v_lshl_or_b32 v90, s69, 8, v161
	v_ashrrev_i32_e32 v91, 31, v90
	v_lshl_add_u64 v[90:91], v[90:91], 2, s[28:29]
	global_load_dwordx4 v[102:105], v[90:91], off
	global_load_dwordx4 v[98:101], v[90:91], off offset:16
	global_load_dwordx4 v[94:97], v[90:91], off offset:512
	s_nop 0
	global_load_dwordx4 v[90:93], v[90:91], off offset:528
	s_mul_i32 s43, s70, 12
	s_add_i32 s60, s43, s69
	s_ashr_i32 s61, s60, 31
	s_lshl_b64 s[60:61], s[60:61], 17
	s_add_u32 s60, s60, 0x1000
	s_addc_u32 s61, s61, 0
	v_lshl_add_u64 v[158:159], v[152:153], 0, s[60:61]
	s_mov_b32 s60, 0xbfb8aa3b
	s_mov_b32 s61, 0xbfb8aa3b
	s_waitcnt vmcnt(0)
	v_pk_mul_f32 v[102:103], v[102:103], s[60:61]
	v_pk_mul_f32 v[104:105], v[104:105], s[60:61]
	v_pk_mul_f32 v[98:99], v[98:99], s[60:61]
	v_pk_mul_f32 v[100:101], v[100:101], s[60:61]
	v_pk_mul_f32 v[94:95], v[94:95], s[60:61]
	v_pk_mul_f32 v[96:97], v[96:97], s[60:61]
	v_pk_mul_f32 v[90:91], v[90:91], s[60:61]
	v_pk_mul_f32 v[92:93], v[92:93], s[60:61]
	v_pk_fma_f32 v[142:143], v[142:143], s[60:61], v[102:103]
	v_pk_fma_f32 v[144:145], v[144:145], s[60:61], v[104:105]
	v_pk_fma_f32 v[138:139], v[138:139], s[60:61], v[98:99]
	v_pk_fma_f32 v[140:141], v[140:141], s[60:61], v[100:101]
	v_exp_f32_e32 v142, v142
	v_exp_f32_e32 v143, v143
	v_exp_f32_e32 v144, v144
	v_exp_f32_e32 v145, v145
	v_exp_f32_e32 v138, v138
	v_exp_f32_e32 v139, v139
	v_exp_f32_e32 v140, v140
	v_exp_f32_e32 v141, v141
	v_pk_add_f32 v[142:143], v[142:143], 1.0 op_sel_hi:[1,0]
	v_pk_add_f32 v[144:145], v[144:145], 1.0 op_sel_hi:[1,0]
	v_pk_add_f32 v[138:139], v[138:139], 1.0 op_sel_hi:[1,0]
	v_pk_add_f32 v[140:141], v[140:141], 1.0 op_sel_hi:[1,0]
	v_min_f32_e32 v142, 0x5d5e0b6b, v142
	v_min_f32_e32 v143, 0x5d5e0b6b, v143
	v_min_f32_e32 v144, 0x5d5e0b6b, v144
	v_min_f32_e32 v145, 0x5d5e0b6b, v145
	v_min_f32_e32 v138, 0x5d5e0b6b, v138
	v_min_f32_e32 v139, 0x5d5e0b6b, v139
	v_min_f32_e32 v140, 0x5d5e0b6b, v140
	v_min_f32_e32 v141, 0x5d5e0b6b, v141
	v_cvt_pk_bf16_f32 v142, v142, v143
	v_cvt_pk_bf16_f32 v143, v144, v145
	v_cvt_pk_bf16_f32 v144, v138, v139
	v_cvt_pk_bf16_f32 v145, v140, v141
	global_store_dwordx4 v[158:159], v[142:145], off offset:-4096 sc1
	v_pk_fma_f32 v[134:135], v[134:135], s[60:61], v[94:95]
	v_pk_fma_f32 v[136:137], v[136:137], s[60:61], v[96:97]
	v_pk_fma_f32 v[130:131], v[130:131], s[60:61], v[90:91]
	v_pk_fma_f32 v[132:133], v[132:133], s[60:61], v[92:93]
	v_exp_f32_e32 v134, v134
	v_exp_f32_e32 v135, v135
	v_exp_f32_e32 v136, v136
	v_exp_f32_e32 v137, v137
	v_exp_f32_e32 v130, v130
	v_exp_f32_e32 v131, v131
	v_exp_f32_e32 v132, v132
	v_exp_f32_e32 v133, v133
	v_pk_add_f32 v[134:135], v[134:135], 1.0 op_sel_hi:[1,0]
	v_pk_add_f32 v[136:137], v[136:137], 1.0 op_sel_hi:[1,0]
	v_pk_add_f32 v[130:131], v[130:131], 1.0 op_sel_hi:[1,0]
	v_pk_add_f32 v[132:133], v[132:133], 1.0 op_sel_hi:[1,0]
	v_min_f32_e32 v134, 0x5d5e0b6b, v134
	v_min_f32_e32 v135, 0x5d5e0b6b, v135
	v_min_f32_e32 v136, 0x5d5e0b6b, v136
	v_min_f32_e32 v137, 0x5d5e0b6b, v137
	v_min_f32_e32 v130, 0x5d5e0b6b, v130
	v_min_f32_e32 v131, 0x5d5e0b6b, v131
	v_min_f32_e32 v132, 0x5d5e0b6b, v132
	v_min_f32_e32 v133, 0x5d5e0b6b, v133
	v_cvt_pk_bf16_f32 v134, v134, v135
	v_cvt_pk_bf16_f32 v135, v136, v137
	v_cvt_pk_bf16_f32 v136, v130, v131
	v_cvt_pk_bf16_f32 v137, v132, v133
	global_store_dwordx4 v[158:159], v[134:137], off offset:-3072 sc1
	v_pk_fma_f32 v[126:127], v[126:127], s[60:61], v[102:103]
	v_pk_fma_f32 v[128:129], v[128:129], s[60:61], v[104:105]
	v_pk_fma_f32 v[122:123], v[122:123], s[60:61], v[98:99]
	v_pk_fma_f32 v[124:125], v[124:125], s[60:61], v[100:101]
	v_exp_f32_e32 v126, v126
	v_exp_f32_e32 v127, v127
	v_exp_f32_e32 v128, v128
	v_exp_f32_e32 v129, v129
	v_exp_f32_e32 v122, v122
	v_exp_f32_e32 v123, v123
	v_exp_f32_e32 v124, v124
	v_exp_f32_e32 v125, v125
	v_pk_add_f32 v[126:127], v[126:127], 1.0 op_sel_hi:[1,0]
	v_pk_add_f32 v[128:129], v[128:129], 1.0 op_sel_hi:[1,0]
	v_pk_add_f32 v[122:123], v[122:123], 1.0 op_sel_hi:[1,0]
	v_pk_add_f32 v[124:125], v[124:125], 1.0 op_sel_hi:[1,0]
	v_min_f32_e32 v126, 0x5d5e0b6b, v126
	v_min_f32_e32 v127, 0x5d5e0b6b, v127
	v_min_f32_e32 v128, 0x5d5e0b6b, v128
	v_min_f32_e32 v129, 0x5d5e0b6b, v129
	v_min_f32_e32 v122, 0x5d5e0b6b, v122
	v_min_f32_e32 v123, 0x5d5e0b6b, v123
	v_min_f32_e32 v124, 0x5d5e0b6b, v124
	v_min_f32_e32 v125, 0x5d5e0b6b, v125
	v_cvt_pk_bf16_f32 v126, v126, v127
	v_cvt_pk_bf16_f32 v127, v128, v129
	v_cvt_pk_bf16_f32 v128, v122, v123
	v_cvt_pk_bf16_f32 v129, v124, v125
	global_store_dwordx4 v[158:159], v[126:129], off offset:-2048 sc1
	v_pk_fma_f32 v[118:119], v[118:119], s[60:61], v[94:95]
	v_pk_fma_f32 v[120:121], v[120:121], s[60:61], v[96:97]
	v_pk_fma_f32 v[114:115], v[114:115], s[60:61], v[90:91]
	v_pk_fma_f32 v[116:117], v[116:117], s[60:61], v[92:93]
	v_exp_f32_e32 v118, v118
	v_exp_f32_e32 v119, v119
	v_exp_f32_e32 v120, v120
	v_exp_f32_e32 v121, v121
	v_exp_f32_e32 v114, v114
	v_exp_f32_e32 v115, v115
	v_exp_f32_e32 v116, v116
	v_exp_f32_e32 v117, v117
	v_pk_add_f32 v[118:119], v[118:119], 1.0 op_sel_hi:[1,0]
	v_pk_add_f32 v[120:121], v[120:121], 1.0 op_sel_hi:[1,0]
	v_pk_add_f32 v[114:115], v[114:115], 1.0 op_sel_hi:[1,0]
	v_pk_add_f32 v[116:117], v[116:117], 1.0 op_sel_hi:[1,0]
	v_min_f32_e32 v118, 0x5d5e0b6b, v118
	v_min_f32_e32 v119, 0x5d5e0b6b, v119
	v_min_f32_e32 v120, 0x5d5e0b6b, v120
	v_min_f32_e32 v121, 0x5d5e0b6b, v121
	v_min_f32_e32 v114, 0x5d5e0b6b, v114
	v_min_f32_e32 v115, 0x5d5e0b6b, v115
	v_min_f32_e32 v116, 0x5d5e0b6b, v116
	v_min_f32_e32 v117, 0x5d5e0b6b, v117
	v_cvt_pk_bf16_f32 v118, v118, v119
	v_cvt_pk_bf16_f32 v119, v120, v121
	v_cvt_pk_bf16_f32 v120, v114, v115
	v_cvt_pk_bf16_f32 v121, v116, v117
	global_store_dwordx4 v[158:159], v[118:121], off offset:-1024 sc1
	v_pk_fma_f32 v[110:111], v[110:111], s[60:61], v[102:103]
	v_pk_fma_f32 v[112:113], v[112:113], s[60:61], v[104:105]
	v_pk_fma_f32 v[106:107], v[106:107], s[60:61], v[98:99]
	v_pk_fma_f32 v[108:109], v[108:109], s[60:61], v[100:101]
	v_exp_f32_e32 v110, v110
	v_exp_f32_e32 v111, v111
	v_exp_f32_e32 v112, v112
	v_exp_f32_e32 v113, v113
	v_exp_f32_e32 v106, v106
	v_exp_f32_e32 v107, v107
	v_exp_f32_e32 v108, v108
	v_exp_f32_e32 v109, v109
	v_pk_add_f32 v[110:111], v[110:111], 1.0 op_sel_hi:[1,0]
	v_pk_add_f32 v[112:113], v[112:113], 1.0 op_sel_hi:[1,0]
	v_pk_add_f32 v[106:107], v[106:107], 1.0 op_sel_hi:[1,0]
	v_pk_add_f32 v[108:109], v[108:109], 1.0 op_sel_hi:[1,0]
	v_min_f32_e32 v110, 0x5d5e0b6b, v110
	v_min_f32_e32 v111, 0x5d5e0b6b, v111
	v_min_f32_e32 v112, 0x5d5e0b6b, v112
	v_min_f32_e32 v113, 0x5d5e0b6b, v113
	v_min_f32_e32 v106, 0x5d5e0b6b, v106
	v_min_f32_e32 v107, 0x5d5e0b6b, v107
	v_min_f32_e32 v108, 0x5d5e0b6b, v108
	v_min_f32_e32 v109, 0x5d5e0b6b, v109
	v_cvt_pk_bf16_f32 v110, v110, v111
	v_cvt_pk_bf16_f32 v111, v112, v113
	v_cvt_pk_bf16_f32 v112, v106, v107
	v_cvt_pk_bf16_f32 v113, v108, v109
	global_store_dwordx4 v[158:159], v[110:113], off sc1
	v_pk_fma_f32 v[86:87], v[86:87], s[60:61], v[94:95]
	v_pk_fma_f32 v[88:89], v[88:89], s[60:61], v[96:97]
	v_pk_fma_f32 v[82:83], v[82:83], s[60:61], v[90:91]
	v_pk_fma_f32 v[84:85], v[84:85], s[60:61], v[92:93]
	v_exp_f32_e32 v86, v86
	v_exp_f32_e32 v87, v87
	v_exp_f32_e32 v88, v88
	v_exp_f32_e32 v89, v89
	v_exp_f32_e32 v82, v82
	v_exp_f32_e32 v83, v83
	v_exp_f32_e32 v84, v84
	v_exp_f32_e32 v85, v85
	v_pk_add_f32 v[86:87], v[86:87], 1.0 op_sel_hi:[1,0]
	v_pk_add_f32 v[88:89], v[88:89], 1.0 op_sel_hi:[1,0]
	v_pk_add_f32 v[82:83], v[82:83], 1.0 op_sel_hi:[1,0]
	v_pk_add_f32 v[84:85], v[84:85], 1.0 op_sel_hi:[1,0]
	v_min_f32_e32 v86, 0x5d5e0b6b, v86
	v_min_f32_e32 v87, 0x5d5e0b6b, v87
	v_min_f32_e32 v88, 0x5d5e0b6b, v88
	v_min_f32_e32 v89, 0x5d5e0b6b, v89
	v_min_f32_e32 v82, 0x5d5e0b6b, v82
	v_min_f32_e32 v83, 0x5d5e0b6b, v83
	v_min_f32_e32 v84, 0x5d5e0b6b, v84
	v_min_f32_e32 v85, 0x5d5e0b6b, v85
	v_cvt_pk_bf16_f32 v86, v86, v87
	v_cvt_pk_bf16_f32 v87, v88, v89
	v_cvt_pk_bf16_f32 v88, v82, v83
	v_cvt_pk_bf16_f32 v89, v84, v85
	global_store_dwordx4 v[158:159], v[86:89], off offset:1024 sc1
	v_pk_fma_f32 v[78:79], v[78:79], s[60:61], v[102:103]
	v_pk_fma_f32 v[80:81], v[80:81], s[60:61], v[104:105]
	v_pk_fma_f32 v[74:75], v[74:75], s[60:61], v[98:99]
	v_pk_fma_f32 v[76:77], v[76:77], s[60:61], v[100:101]
	v_exp_f32_e32 v78, v78
	v_exp_f32_e32 v79, v79
	v_exp_f32_e32 v80, v80
	v_exp_f32_e32 v81, v81
	v_exp_f32_e32 v74, v74
	v_exp_f32_e32 v75, v75
	v_exp_f32_e32 v76, v76
	v_exp_f32_e32 v77, v77
	v_pk_add_f32 v[78:79], v[78:79], 1.0 op_sel_hi:[1,0]
	v_pk_add_f32 v[80:81], v[80:81], 1.0 op_sel_hi:[1,0]
	v_pk_add_f32 v[74:75], v[74:75], 1.0 op_sel_hi:[1,0]
	v_pk_add_f32 v[76:77], v[76:77], 1.0 op_sel_hi:[1,0]
	v_min_f32_e32 v78, 0x5d5e0b6b, v78
	v_min_f32_e32 v79, 0x5d5e0b6b, v79
	v_min_f32_e32 v80, 0x5d5e0b6b, v80
	v_min_f32_e32 v81, 0x5d5e0b6b, v81
	v_min_f32_e32 v74, 0x5d5e0b6b, v74
	v_min_f32_e32 v75, 0x5d5e0b6b, v75
	v_min_f32_e32 v76, 0x5d5e0b6b, v76
	v_min_f32_e32 v77, 0x5d5e0b6b, v77
	v_cvt_pk_bf16_f32 v78, v78, v79
	v_cvt_pk_bf16_f32 v79, v80, v81
	v_cvt_pk_bf16_f32 v80, v74, v75
	v_cvt_pk_bf16_f32 v81, v76, v77
	global_store_dwordx4 v[158:159], v[78:81], off offset:2048 sc1
	v_pk_fma_f32 v[70:71], v[70:71], s[60:61], v[94:95]
	v_pk_fma_f32 v[72:73], v[72:73], s[60:61], v[96:97]
	v_pk_fma_f32 v[66:67], v[66:67], s[60:61], v[90:91]
	v_pk_fma_f32 v[68:69], v[68:69], s[60:61], v[92:93]
	v_exp_f32_e32 v70, v70
	v_exp_f32_e32 v71, v71
	v_exp_f32_e32 v72, v72
	v_exp_f32_e32 v73, v73
	v_exp_f32_e32 v66, v66
	v_exp_f32_e32 v67, v67
	v_exp_f32_e32 v68, v68
	v_exp_f32_e32 v69, v69
	v_pk_add_f32 v[70:71], v[70:71], 1.0 op_sel_hi:[1,0]
	v_pk_add_f32 v[72:73], v[72:73], 1.0 op_sel_hi:[1,0]
	v_pk_add_f32 v[66:67], v[66:67], 1.0 op_sel_hi:[1,0]
	v_pk_add_f32 v[68:69], v[68:69], 1.0 op_sel_hi:[1,0]
	v_min_f32_e32 v70, 0x5d5e0b6b, v70
	v_min_f32_e32 v71, 0x5d5e0b6b, v71
	v_min_f32_e32 v72, 0x5d5e0b6b, v72
	v_min_f32_e32 v73, 0x5d5e0b6b, v73
	v_min_f32_e32 v66, 0x5d5e0b6b, v66
	v_min_f32_e32 v67, 0x5d5e0b6b, v67
	v_min_f32_e32 v68, 0x5d5e0b6b, v68
	v_min_f32_e32 v69, 0x5d5e0b6b, v69
	v_cvt_pk_bf16_f32 v70, v70, v71
	v_cvt_pk_bf16_f32 v71, v72, v73
	v_cvt_pk_bf16_f32 v72, v66, v67
	v_cvt_pk_bf16_f32 v73, v68, v69
	global_store_dwordx4 v[158:159], v[70:73], off offset:3072 sc1
	v_add_co_u32_e32 v158, vcc, 0x2000, v158
	s_nop 1
	v_addc_co_u32_e32 v159, vcc, 0, v159, vcc
	v_pk_fma_f32 v[62:63], v[62:63], s[60:61], v[102:103]
	v_pk_fma_f32 v[64:65], v[64:65], s[60:61], v[104:105]
	v_pk_fma_f32 v[58:59], v[58:59], s[60:61], v[98:99]
	v_pk_fma_f32 v[60:61], v[60:61], s[60:61], v[100:101]
	v_exp_f32_e32 v62, v62
	v_exp_f32_e32 v63, v63
	v_exp_f32_e32 v64, v64
	v_exp_f32_e32 v65, v65
	v_exp_f32_e32 v58, v58
	v_exp_f32_e32 v59, v59
	v_exp_f32_e32 v60, v60
	v_exp_f32_e32 v61, v61
	v_pk_add_f32 v[62:63], v[62:63], 1.0 op_sel_hi:[1,0]
	v_pk_add_f32 v[64:65], v[64:65], 1.0 op_sel_hi:[1,0]
	v_pk_add_f32 v[58:59], v[58:59], 1.0 op_sel_hi:[1,0]
	v_pk_add_f32 v[60:61], v[60:61], 1.0 op_sel_hi:[1,0]
	v_min_f32_e32 v62, 0x5d5e0b6b, v62
	v_min_f32_e32 v63, 0x5d5e0b6b, v63
	v_min_f32_e32 v64, 0x5d5e0b6b, v64
	v_min_f32_e32 v65, 0x5d5e0b6b, v65
	v_min_f32_e32 v58, 0x5d5e0b6b, v58
	v_min_f32_e32 v59, 0x5d5e0b6b, v59
	v_min_f32_e32 v60, 0x5d5e0b6b, v60
	v_min_f32_e32 v61, 0x5d5e0b6b, v61
	v_cvt_pk_bf16_f32 v62, v62, v63
	v_cvt_pk_bf16_f32 v63, v64, v65
	v_cvt_pk_bf16_f32 v64, v58, v59
	v_cvt_pk_bf16_f32 v65, v60, v61
	global_store_dwordx4 v[158:159], v[62:65], off offset:-4096 sc1
	v_pk_fma_f32 v[54:55], v[54:55], s[60:61], v[94:95]
	v_pk_fma_f32 v[56:57], v[56:57], s[60:61], v[96:97]
	v_pk_fma_f32 v[50:51], v[50:51], s[60:61], v[90:91]
	v_pk_fma_f32 v[52:53], v[52:53], s[60:61], v[92:93]
	v_exp_f32_e32 v54, v54
	v_exp_f32_e32 v55, v55
	v_exp_f32_e32 v56, v56
	v_exp_f32_e32 v57, v57
	v_exp_f32_e32 v50, v50
	v_exp_f32_e32 v51, v51
	v_exp_f32_e32 v52, v52
	v_exp_f32_e32 v53, v53
	v_pk_add_f32 v[54:55], v[54:55], 1.0 op_sel_hi:[1,0]
	v_pk_add_f32 v[56:57], v[56:57], 1.0 op_sel_hi:[1,0]
	v_pk_add_f32 v[50:51], v[50:51], 1.0 op_sel_hi:[1,0]
	v_pk_add_f32 v[52:53], v[52:53], 1.0 op_sel_hi:[1,0]
	v_min_f32_e32 v54, 0x5d5e0b6b, v54
	v_min_f32_e32 v55, 0x5d5e0b6b, v55
	v_min_f32_e32 v56, 0x5d5e0b6b, v56
	v_min_f32_e32 v57, 0x5d5e0b6b, v57
	v_min_f32_e32 v50, 0x5d5e0b6b, v50
	v_min_f32_e32 v51, 0x5d5e0b6b, v51
	v_min_f32_e32 v52, 0x5d5e0b6b, v52
	v_min_f32_e32 v53, 0x5d5e0b6b, v53
	v_cvt_pk_bf16_f32 v54, v54, v55
	v_cvt_pk_bf16_f32 v55, v56, v57
	v_cvt_pk_bf16_f32 v56, v50, v51
	v_cvt_pk_bf16_f32 v57, v52, v53
	global_store_dwordx4 v[158:159], v[54:57], off offset:-3072 sc1
	v_pk_fma_f32 v[46:47], v[46:47], s[60:61], v[102:103]
	v_pk_fma_f32 v[48:49], v[48:49], s[60:61], v[104:105]
	v_pk_fma_f32 v[42:43], v[42:43], s[60:61], v[98:99]
	v_pk_fma_f32 v[44:45], v[44:45], s[60:61], v[100:101]
	v_exp_f32_e32 v46, v46
	v_exp_f32_e32 v47, v47
	v_exp_f32_e32 v48, v48
	v_exp_f32_e32 v49, v49
	v_exp_f32_e32 v42, v42
	v_exp_f32_e32 v43, v43
	v_exp_f32_e32 v44, v44
	v_exp_f32_e32 v45, v45
	v_pk_add_f32 v[46:47], v[46:47], 1.0 op_sel_hi:[1,0]
	v_pk_add_f32 v[48:49], v[48:49], 1.0 op_sel_hi:[1,0]
	v_pk_add_f32 v[42:43], v[42:43], 1.0 op_sel_hi:[1,0]
	v_pk_add_f32 v[44:45], v[44:45], 1.0 op_sel_hi:[1,0]
	v_min_f32_e32 v46, 0x5d5e0b6b, v46
	v_min_f32_e32 v47, 0x5d5e0b6b, v47
	v_min_f32_e32 v48, 0x5d5e0b6b, v48
	v_min_f32_e32 v49, 0x5d5e0b6b, v49
	v_min_f32_e32 v42, 0x5d5e0b6b, v42
	v_min_f32_e32 v43, 0x5d5e0b6b, v43
	v_min_f32_e32 v44, 0x5d5e0b6b, v44
	v_min_f32_e32 v45, 0x5d5e0b6b, v45
	v_cvt_pk_bf16_f32 v46, v46, v47
	v_cvt_pk_bf16_f32 v47, v48, v49
	v_cvt_pk_bf16_f32 v48, v42, v43
	v_cvt_pk_bf16_f32 v49, v44, v45
	global_store_dwordx4 v[158:159], v[46:49], off offset:-2048 sc1
	v_pk_fma_f32 v[38:39], v[38:39], s[60:61], v[94:95]
	v_pk_fma_f32 v[40:41], v[40:41], s[60:61], v[96:97]
	v_pk_fma_f32 v[34:35], v[34:35], s[60:61], v[90:91]
	v_pk_fma_f32 v[36:37], v[36:37], s[60:61], v[92:93]
	v_exp_f32_e32 v38, v38
	v_exp_f32_e32 v39, v39
	v_exp_f32_e32 v40, v40
	v_exp_f32_e32 v41, v41
	v_exp_f32_e32 v34, v34
	v_exp_f32_e32 v35, v35
	v_exp_f32_e32 v36, v36
	v_exp_f32_e32 v37, v37
	v_pk_add_f32 v[38:39], v[38:39], 1.0 op_sel_hi:[1,0]
	v_pk_add_f32 v[40:41], v[40:41], 1.0 op_sel_hi:[1,0]
	v_pk_add_f32 v[34:35], v[34:35], 1.0 op_sel_hi:[1,0]
	v_pk_add_f32 v[36:37], v[36:37], 1.0 op_sel_hi:[1,0]
	v_min_f32_e32 v38, 0x5d5e0b6b, v38
	v_min_f32_e32 v39, 0x5d5e0b6b, v39
	v_min_f32_e32 v40, 0x5d5e0b6b, v40
	v_min_f32_e32 v41, 0x5d5e0b6b, v41
	v_min_f32_e32 v34, 0x5d5e0b6b, v34
	v_min_f32_e32 v35, 0x5d5e0b6b, v35
	v_min_f32_e32 v36, 0x5d5e0b6b, v36
	v_min_f32_e32 v37, 0x5d5e0b6b, v37
	v_cvt_pk_bf16_f32 v38, v38, v39
	v_cvt_pk_bf16_f32 v39, v40, v41
	v_cvt_pk_bf16_f32 v40, v34, v35
	v_cvt_pk_bf16_f32 v41, v36, v37
	global_store_dwordx4 v[158:159], v[38:41], off offset:-1024 sc1
	v_pk_fma_f32 v[30:31], v[30:31], s[60:61], v[102:103]
	v_pk_fma_f32 v[32:33], v[32:33], s[60:61], v[104:105]
	v_pk_fma_f32 v[26:27], v[26:27], s[60:61], v[98:99]
	v_pk_fma_f32 v[28:29], v[28:29], s[60:61], v[100:101]
	v_exp_f32_e32 v30, v30
	v_exp_f32_e32 v31, v31
	v_exp_f32_e32 v32, v32
	v_exp_f32_e32 v33, v33
	v_exp_f32_e32 v26, v26
	v_exp_f32_e32 v27, v27
	v_exp_f32_e32 v28, v28
	v_exp_f32_e32 v29, v29
	v_pk_add_f32 v[30:31], v[30:31], 1.0 op_sel_hi:[1,0]
	v_pk_add_f32 v[32:33], v[32:33], 1.0 op_sel_hi:[1,0]
	v_pk_add_f32 v[26:27], v[26:27], 1.0 op_sel_hi:[1,0]
	v_pk_add_f32 v[28:29], v[28:29], 1.0 op_sel_hi:[1,0]
	v_min_f32_e32 v30, 0x5d5e0b6b, v30
	v_min_f32_e32 v31, 0x5d5e0b6b, v31
	v_min_f32_e32 v32, 0x5d5e0b6b, v32
	v_min_f32_e32 v33, 0x5d5e0b6b, v33
	v_min_f32_e32 v26, 0x5d5e0b6b, v26
	v_min_f32_e32 v27, 0x5d5e0b6b, v27
	v_min_f32_e32 v28, 0x5d5e0b6b, v28
	v_min_f32_e32 v29, 0x5d5e0b6b, v29
	v_cvt_pk_bf16_f32 v30, v30, v31
	v_cvt_pk_bf16_f32 v31, v32, v33
	v_cvt_pk_bf16_f32 v32, v26, v27
	v_cvt_pk_bf16_f32 v33, v28, v29
	global_store_dwordx4 v[158:159], v[30:33], off sc1
	v_pk_fma_f32 v[22:23], v[22:23], s[60:61], v[94:95]
	v_pk_fma_f32 v[24:25], v[24:25], s[60:61], v[96:97]
	v_pk_fma_f32 v[18:19], v[18:19], s[60:61], v[90:91]
	v_pk_fma_f32 v[20:21], v[20:21], s[60:61], v[92:93]
	v_exp_f32_e32 v22, v22
	v_exp_f32_e32 v23, v23
	v_exp_f32_e32 v24, v24
	v_exp_f32_e32 v25, v25
	v_exp_f32_e32 v18, v18
	v_exp_f32_e32 v19, v19
	v_exp_f32_e32 v20, v20
	v_exp_f32_e32 v21, v21
	v_pk_add_f32 v[22:23], v[22:23], 1.0 op_sel_hi:[1,0]
	v_pk_add_f32 v[24:25], v[24:25], 1.0 op_sel_hi:[1,0]
	v_pk_add_f32 v[18:19], v[18:19], 1.0 op_sel_hi:[1,0]
	v_pk_add_f32 v[20:21], v[20:21], 1.0 op_sel_hi:[1,0]
	v_min_f32_e32 v22, 0x5d5e0b6b, v22
	v_min_f32_e32 v23, 0x5d5e0b6b, v23
	v_min_f32_e32 v24, 0x5d5e0b6b, v24
	v_min_f32_e32 v25, 0x5d5e0b6b, v25
	v_min_f32_e32 v18, 0x5d5e0b6b, v18
	v_min_f32_e32 v19, 0x5d5e0b6b, v19
	v_min_f32_e32 v20, 0x5d5e0b6b, v20
	v_min_f32_e32 v21, 0x5d5e0b6b, v21
	v_cvt_pk_bf16_f32 v22, v22, v23
	v_cvt_pk_bf16_f32 v23, v24, v25
	v_cvt_pk_bf16_f32 v24, v18, v19
	v_cvt_pk_bf16_f32 v25, v20, v21
	global_store_dwordx4 v[158:159], v[22:25], off offset:1024 sc1
	v_pk_fma_f32 v[14:15], v[14:15], s[60:61], v[102:103]
	v_pk_fma_f32 v[16:17], v[16:17], s[60:61], v[104:105]
	v_pk_fma_f32 v[10:11], v[10:11], s[60:61], v[98:99]
	v_pk_fma_f32 v[12:13], v[12:13], s[60:61], v[100:101]
	v_exp_f32_e32 v14, v14
	v_exp_f32_e32 v15, v15
	v_exp_f32_e32 v16, v16
	v_exp_f32_e32 v17, v17
	v_exp_f32_e32 v10, v10
	v_exp_f32_e32 v11, v11
	v_exp_f32_e32 v12, v12
	v_exp_f32_e32 v13, v13
	v_pk_add_f32 v[14:15], v[14:15], 1.0 op_sel_hi:[1,0]
	v_pk_add_f32 v[16:17], v[16:17], 1.0 op_sel_hi:[1,0]
	v_pk_add_f32 v[10:11], v[10:11], 1.0 op_sel_hi:[1,0]
	v_pk_add_f32 v[12:13], v[12:13], 1.0 op_sel_hi:[1,0]
	v_min_f32_e32 v14, 0x5d5e0b6b, v14
	v_min_f32_e32 v15, 0x5d5e0b6b, v15
	v_min_f32_e32 v16, 0x5d5e0b6b, v16
	v_min_f32_e32 v17, 0x5d5e0b6b, v17
	v_min_f32_e32 v10, 0x5d5e0b6b, v10
	v_min_f32_e32 v11, 0x5d5e0b6b, v11
	v_min_f32_e32 v12, 0x5d5e0b6b, v12
	v_min_f32_e32 v13, 0x5d5e0b6b, v13
	v_cvt_pk_bf16_f32 v14, v14, v15
	v_cvt_pk_bf16_f32 v15, v16, v17
	v_cvt_pk_bf16_f32 v16, v10, v11
	v_cvt_pk_bf16_f32 v17, v12, v13
	global_store_dwordx4 v[158:159], v[14:17], off offset:2048 sc1
	v_pk_fma_f32 v[6:7], v[6:7], s[60:61], v[94:95]
	v_pk_fma_f32 v[8:9], v[8:9], s[60:61], v[96:97]
	v_pk_fma_f32 v[2:3], v[2:3], s[60:61], v[90:91]
	v_pk_fma_f32 v[4:5], v[4:5], s[60:61], v[92:93]
	v_exp_f32_e32 v6, v6
	v_exp_f32_e32 v7, v7
	v_exp_f32_e32 v8, v8
	v_exp_f32_e32 v9, v9
	v_exp_f32_e32 v2, v2
	v_exp_f32_e32 v3, v3
	v_exp_f32_e32 v4, v4
	v_exp_f32_e32 v5, v5
	v_pk_add_f32 v[6:7], v[6:7], 1.0 op_sel_hi:[1,0]
	v_pk_add_f32 v[8:9], v[8:9], 1.0 op_sel_hi:[1,0]
	v_pk_add_f32 v[2:3], v[2:3], 1.0 op_sel_hi:[1,0]
	v_pk_add_f32 v[4:5], v[4:5], 1.0 op_sel_hi:[1,0]
	v_min_f32_e32 v6, 0x5d5e0b6b, v6
	v_min_f32_e32 v7, 0x5d5e0b6b, v7
	v_min_f32_e32 v8, 0x5d5e0b6b, v8
	v_min_f32_e32 v9, 0x5d5e0b6b, v9
	v_min_f32_e32 v2, 0x5d5e0b6b, v2
	v_min_f32_e32 v3, 0x5d5e0b6b, v3
	v_min_f32_e32 v4, 0x5d5e0b6b, v4
	v_min_f32_e32 v5, 0x5d5e0b6b, v5
	v_cvt_pk_bf16_f32 v6, v6, v7
	v_cvt_pk_bf16_f32 v7, v8, v9
	v_cvt_pk_bf16_f32 v8, v2, v3
	v_cvt_pk_bf16_f32 v9, v4, v5
	global_store_dwordx4 v[158:159], v[6:9], off offset:3072 sc1
	s_andn2_b64 vcc, exec, s[38:39]
	s_mov_b64 s[38:39], -1
	s_cbranch_vccnz .LBB0_533
	s_andn2_b64 vcc, exec, s[26:27]
	s_cbranch_vccnz .LBB0_532
	s_barrier
	s_branch .LBB0_532

.LBB0_619:
	s_cmp_gt_i32 s73, 1
	s_cselect_b64 s[60:61], -1, 0
	s_mov_b64 s[62:63], -1
	s_and_b64 vcc, exec, s[60:61]
	s_mul_i32 s47, s75, 12
	s_cbranch_vccz .LBB0_622
	s_add_i32 s62, s74, s47
	s_add_i32 s62, s62, 8
	s_ashr_i32 s63, s62, 31
	s_lshl_b64 s[62:63], s[62:63], 17
	s_add_u32 s62, s62, 0x1000
	s_addc_u32 s63, s63, 0
	v_lshl_add_u64 v[158:159], v[148:149], 0, s[62:63]
	s_mov_b64 s[62:63], 0x2000
	global_load_dwordx4 v[164:167], v[158:159], off offset:-4096
	global_load_dwordx4 v[168:171], v[158:159], off offset:-3072
	global_load_dwordx4 v[172:175], v[158:159], off offset:-2048
	global_load_dwordx4 v[176:179], v[158:159], off offset:-1024
	global_load_dwordx4 v[180:183], v[158:159], off
	global_load_dwordx4 v[184:187], v[158:159], off offset:1024
	global_load_dwordx4 v[188:191], v[158:159], off offset:2048
	global_load_dwordx4 v[192:195], v[158:159], off offset:3072
	v_lshl_add_u64 v[158:159], v[158:159], 0, s[62:63]
	v_lshl_add_u32 v132, s75, 8, v160
	v_lshl_or_b32 v2, s74, 8, v162
	v_ashrrev_i32_e32 v133, 31, v132
	v_ashrrev_i32_e32 v3, 31, v2
	v_lshlrev_b64 v[132:133], 11, v[132:133]
	v_lshlrev_b64 v[134:135], 1, v[2:3]
	v_lshl_add_u64 v[2:3], s[28:29], 0, v[132:133]
	v_lshl_add_u64 v[2:3], v[2:3], 0, v[134:135]
	global_load_dwordx4 v[206:209], v[158:159], off offset:-4096
	global_load_dwordx4 v[210:213], v[158:159], off offset:-3072
	global_load_dwordx4 v[214:217], v[158:159], off offset:-2048
	global_load_dwordx4 v[218:221], v[158:159], off offset:-1024
	global_load_dwordx4 v[154:157], v[158:159], off
	global_load_dwordx4 v[232:235], v[158:159], off offset:1024
	s_mov_b64 s[62:63], 0x8000
	s_mov_b64 s[64:65], 0x28000
	s_waitcnt vmcnt(13)
	v_lshlrev_b32_e32 v132, 16, v164
	v_and_b32_e32 v133, 0xffff0000, v164
	v_lshlrev_b32_e32 v134, 16, v165
	v_and_b32_e32 v135, 0xffff0000, v165
	v_rcp_f32_e32 v132, v132
	v_rcp_f32_e32 v133, v133
	v_rcp_f32_e32 v134, v134
	v_rcp_f32_e32 v135, v135
	v_pk_mul_f32 v[132:133], v[128:129], v[132:133]
	v_pk_mul_f32 v[134:135], v[130:131], v[134:135]
	v_cvt_pk_bf16_f32 v136, v132, v133
	v_cvt_pk_bf16_f32 v137, v134, v135
	v_lshlrev_b32_e32 v132, 16, v166
	v_and_b32_e32 v133, 0xffff0000, v166
	v_lshlrev_b32_e32 v134, 16, v167
	v_and_b32_e32 v135, 0xffff0000, v167
	v_rcp_f32_e32 v132, v132
	v_rcp_f32_e32 v133, v133
	v_rcp_f32_e32 v134, v134
	v_rcp_f32_e32 v135, v135
	v_pk_mul_f32 v[132:133], v[124:125], v[132:133]
	v_pk_mul_f32 v[134:135], v[126:127], v[134:135]
	v_cvt_pk_bf16_f32 v138, v132, v133
	v_cvt_pk_bf16_f32 v139, v134, v135
	global_store_dwordx4 v[2:3], v[136:139], off sc1
	global_load_dwordx4 v[164:167], v[158:159], off offset:2048
	s_waitcnt vmcnt(14)
	v_lshlrev_b32_e32 v132, 16, v168
	v_and_b32_e32 v133, 0xffff0000, v168
	v_lshlrev_b32_e32 v134, 16, v169
	v_and_b32_e32 v135, 0xffff0000, v169
	v_rcp_f32_e32 v132, v132
	v_rcp_f32_e32 v133, v133
	v_rcp_f32_e32 v134, v134
	v_rcp_f32_e32 v135, v135
	v_pk_mul_f32 v[132:133], v[96:97], v[132:133]
	v_pk_mul_f32 v[134:135], v[98:99], v[134:135]
	v_cvt_pk_bf16_f32 v136, v132, v133
	v_cvt_pk_bf16_f32 v137, v134, v135
	v_lshlrev_b32_e32 v132, 16, v170
	v_and_b32_e32 v133, 0xffff0000, v170
	v_lshlrev_b32_e32 v134, 16, v171
	v_and_b32_e32 v135, 0xffff0000, v171
	v_rcp_f32_e32 v132, v132
	v_rcp_f32_e32 v133, v133
	v_rcp_f32_e32 v134, v134
	v_rcp_f32_e32 v135, v135
	v_pk_mul_f32 v[132:133], v[92:93], v[132:133]
	v_pk_mul_f32 v[134:135], v[94:95], v[134:135]
	v_cvt_pk_bf16_f32 v138, v132, v133
	v_cvt_pk_bf16_f32 v139, v134, v135
	global_store_dwordx4 v[2:3], v[136:139], off offset:256 sc1
	v_lshl_add_u64 v[2:3], v[2:3], 0, s[62:63]
	global_load_dwordx4 v[168:171], v[158:159], off offset:3072
	s_waitcnt vmcnt(15)
	v_lshlrev_b32_e32 v132, 16, v172
	v_and_b32_e32 v133, 0xffff0000, v172
	v_lshlrev_b32_e32 v134, 16, v173
	v_and_b32_e32 v135, 0xffff0000, v173
	v_rcp_f32_e32 v132, v132
	v_rcp_f32_e32 v133, v133
	v_rcp_f32_e32 v134, v134
	v_rcp_f32_e32 v135, v135
	v_pk_mul_f32 v[132:133], v[120:121], v[132:133]
	v_pk_mul_f32 v[134:135], v[122:123], v[134:135]
	v_cvt_pk_bf16_f32 v136, v132, v133
	v_cvt_pk_bf16_f32 v137, v134, v135
	v_lshlrev_b32_e32 v132, 16, v174
	v_and_b32_e32 v133, 0xffff0000, v174
	v_lshlrev_b32_e32 v134, 16, v175
	v_and_b32_e32 v135, 0xffff0000, v175
	v_rcp_f32_e32 v132, v132
	v_rcp_f32_e32 v133, v133
	v_rcp_f32_e32 v134, v134
	v_rcp_f32_e32 v135, v135
	v_pk_mul_f32 v[132:133], v[116:117], v[132:133]
	v_pk_mul_f32 v[134:135], v[118:119], v[134:135]
	v_cvt_pk_bf16_f32 v138, v132, v133
	v_cvt_pk_bf16_f32 v139, v134, v135
	global_store_dwordx4 v[2:3], v[136:139], off sc1
	s_waitcnt vmcnt(15)
	v_lshlrev_b32_e32 v132, 16, v176
	v_and_b32_e32 v133, 0xffff0000, v176
	v_lshlrev_b32_e32 v134, 16, v177
	v_and_b32_e32 v135, 0xffff0000, v177
	v_rcp_f32_e32 v132, v132
	v_rcp_f32_e32 v133, v133
	v_rcp_f32_e32 v134, v134
	v_rcp_f32_e32 v135, v135
	v_pk_mul_f32 v[132:133], v[88:89], v[132:133]
	v_pk_mul_f32 v[134:135], v[90:91], v[134:135]
	v_cvt_pk_bf16_f32 v136, v132, v133
	v_cvt_pk_bf16_f32 v137, v134, v135
	v_lshlrev_b32_e32 v132, 16, v178
	v_and_b32_e32 v133, 0xffff0000, v178
	v_lshlrev_b32_e32 v134, 16, v179
	v_and_b32_e32 v135, 0xffff0000, v179
	v_rcp_f32_e32 v132, v132
	v_rcp_f32_e32 v133, v133
	v_rcp_f32_e32 v134, v134
	v_rcp_f32_e32 v135, v135
	v_pk_mul_f32 v[132:133], v[84:85], v[132:133]
	v_pk_mul_f32 v[134:135], v[86:87], v[134:135]
	v_cvt_pk_bf16_f32 v138, v132, v133
	v_cvt_pk_bf16_f32 v139, v134, v135
	global_store_dwordx4 v[2:3], v[136:139], off offset:256 sc1
	v_lshl_add_u64 v[2:3], v[2:3], 0, s[62:63]
	s_waitcnt vmcnt(15)
	v_lshlrev_b32_e32 v132, 16, v180
	v_and_b32_e32 v133, 0xffff0000, v180
	v_lshlrev_b32_e32 v134, 16, v181
	v_and_b32_e32 v135, 0xffff0000, v181
	v_rcp_f32_e32 v132, v132
	v_rcp_f32_e32 v133, v133
	v_rcp_f32_e32 v134, v134
	v_rcp_f32_e32 v135, v135
	v_pk_mul_f32 v[132:133], v[112:113], v[132:133]
	v_pk_mul_f32 v[134:135], v[114:115], v[134:135]
	v_cvt_pk_bf16_f32 v136, v132, v133
	v_cvt_pk_bf16_f32 v137, v134, v135
	v_lshlrev_b32_e32 v132, 16, v182
	v_and_b32_e32 v133, 0xffff0000, v182
	v_lshlrev_b32_e32 v134, 16, v183
	v_and_b32_e32 v135, 0xffff0000, v183
	v_rcp_f32_e32 v132, v132
	v_rcp_f32_e32 v133, v133
	v_rcp_f32_e32 v134, v134
	v_rcp_f32_e32 v135, v135
	v_pk_mul_f32 v[132:133], v[108:109], v[132:133]
	v_pk_mul_f32 v[134:135], v[110:111], v[134:135]
	v_cvt_pk_bf16_f32 v138, v132, v133
	v_cvt_pk_bf16_f32 v139, v134, v135
	global_store_dwordx4 v[2:3], v[136:139], off sc1
	s_waitcnt vmcnt(15)
	v_lshlrev_b32_e32 v132, 16, v184
	v_and_b32_e32 v133, 0xffff0000, v184
	v_lshlrev_b32_e32 v134, 16, v185
	v_and_b32_e32 v135, 0xffff0000, v185
	v_rcp_f32_e32 v132, v132
	v_rcp_f32_e32 v133, v133
	v_rcp_f32_e32 v134, v134
	v_rcp_f32_e32 v135, v135
	v_pk_mul_f32 v[132:133], v[80:81], v[132:133]
	v_pk_mul_f32 v[134:135], v[82:83], v[134:135]
	v_cvt_pk_bf16_f32 v136, v132, v133
	v_cvt_pk_bf16_f32 v137, v134, v135
	v_lshlrev_b32_e32 v132, 16, v186
	v_and_b32_e32 v133, 0xffff0000, v186
	v_lshlrev_b32_e32 v134, 16, v187
	v_and_b32_e32 v135, 0xffff0000, v187
	v_rcp_f32_e32 v132, v132
	v_rcp_f32_e32 v133, v133
	v_rcp_f32_e32 v134, v134
	v_rcp_f32_e32 v135, v135
	v_pk_mul_f32 v[132:133], v[76:77], v[132:133]
	v_pk_mul_f32 v[134:135], v[78:79], v[134:135]
	v_cvt_pk_bf16_f32 v138, v132, v133
	v_cvt_pk_bf16_f32 v139, v134, v135
	global_store_dwordx4 v[2:3], v[136:139], off offset:256 sc1
	v_lshl_add_u64 v[2:3], v[2:3], 0, s[62:63]
	s_waitcnt vmcnt(15)
	v_lshlrev_b32_e32 v132, 16, v188
	v_and_b32_e32 v133, 0xffff0000, v188
	v_lshlrev_b32_e32 v134, 16, v189
	v_and_b32_e32 v135, 0xffff0000, v189
	v_rcp_f32_e32 v132, v132
	v_rcp_f32_e32 v133, v133
	v_rcp_f32_e32 v134, v134
	v_rcp_f32_e32 v135, v135
	v_pk_mul_f32 v[132:133], v[104:105], v[132:133]
	v_pk_mul_f32 v[134:135], v[106:107], v[134:135]
	v_cvt_pk_bf16_f32 v136, v132, v133
	v_cvt_pk_bf16_f32 v137, v134, v135
	v_lshlrev_b32_e32 v132, 16, v190
	v_and_b32_e32 v133, 0xffff0000, v190
	v_lshlrev_b32_e32 v134, 16, v191
	v_and_b32_e32 v135, 0xffff0000, v191
	v_rcp_f32_e32 v132, v132
	v_rcp_f32_e32 v133, v133
	v_rcp_f32_e32 v134, v134
	v_rcp_f32_e32 v135, v135
	v_pk_mul_f32 v[132:133], v[100:101], v[132:133]
	v_pk_mul_f32 v[134:135], v[102:103], v[134:135]
	v_cvt_pk_bf16_f32 v138, v132, v133
	v_cvt_pk_bf16_f32 v139, v134, v135
	global_store_dwordx4 v[2:3], v[136:139], off sc1
	s_waitcnt vmcnt(15)
	v_lshlrev_b32_e32 v132, 16, v192
	v_and_b32_e32 v133, 0xffff0000, v192
	v_lshlrev_b32_e32 v134, 16, v193
	v_and_b32_e32 v135, 0xffff0000, v193
	v_rcp_f32_e32 v132, v132
	v_rcp_f32_e32 v133, v133
	v_rcp_f32_e32 v134, v134
	v_rcp_f32_e32 v135, v135
	v_pk_mul_f32 v[132:133], v[72:73], v[132:133]
	v_pk_mul_f32 v[134:135], v[74:75], v[134:135]
	v_cvt_pk_bf16_f32 v136, v132, v133
	v_cvt_pk_bf16_f32 v137, v134, v135
	v_lshlrev_b32_e32 v132, 16, v194
	v_and_b32_e32 v133, 0xffff0000, v194
	v_lshlrev_b32_e32 v134, 16, v195
	v_and_b32_e32 v135, 0xffff0000, v195
	v_rcp_f32_e32 v132, v132
	v_rcp_f32_e32 v133, v133
	v_rcp_f32_e32 v134, v134
	v_rcp_f32_e32 v135, v135
	v_pk_mul_f32 v[132:133], v[68:69], v[132:133]
	v_pk_mul_f32 v[134:135], v[70:71], v[134:135]
	v_cvt_pk_bf16_f32 v138, v132, v133
	v_cvt_pk_bf16_f32 v139, v134, v135
	global_store_dwordx4 v[2:3], v[136:139], off offset:256 sc1
	v_lshl_add_u64 v[2:3], v[2:3], 0, s[64:65]
	s_waitcnt vmcnt(15)
	v_lshlrev_b32_e32 v132, 16, v206
	v_and_b32_e32 v133, 0xffff0000, v206
	v_lshlrev_b32_e32 v134, 16, v207
	v_and_b32_e32 v135, 0xffff0000, v207
	v_rcp_f32_e32 v132, v132
	v_rcp_f32_e32 v133, v133
	v_rcp_f32_e32 v134, v134
	v_rcp_f32_e32 v135, v135
	v_pk_mul_f32 v[132:133], v[64:65], v[132:133]
	v_pk_mul_f32 v[134:135], v[66:67], v[134:135]
	v_cvt_pk_bf16_f32 v136, v132, v133
	v_cvt_pk_bf16_f32 v137, v134, v135
	v_lshlrev_b32_e32 v132, 16, v208
	v_and_b32_e32 v133, 0xffff0000, v208
	v_lshlrev_b32_e32 v134, 16, v209
	v_and_b32_e32 v135, 0xffff0000, v209
	v_rcp_f32_e32 v132, v132
	v_rcp_f32_e32 v133, v133
	v_rcp_f32_e32 v134, v134
	v_rcp_f32_e32 v135, v135
	v_pk_mul_f32 v[132:133], v[60:61], v[132:133]
	v_pk_mul_f32 v[134:135], v[62:63], v[134:135]
	v_cvt_pk_bf16_f32 v138, v132, v133
	v_cvt_pk_bf16_f32 v139, v134, v135
	global_store_dwordx4 v[2:3], v[136:139], off sc1
	s_waitcnt vmcnt(15)
	v_lshlrev_b32_e32 v132, 16, v210
	v_and_b32_e32 v133, 0xffff0000, v210
	v_lshlrev_b32_e32 v134, 16, v211
	v_and_b32_e32 v135, 0xffff0000, v211
	v_rcp_f32_e32 v132, v132
	v_rcp_f32_e32 v133, v133
	v_rcp_f32_e32 v134, v134
	v_rcp_f32_e32 v135, v135
	v_pk_mul_f32 v[132:133], v[32:33], v[132:133]
	v_pk_mul_f32 v[134:135], v[34:35], v[134:135]
	v_cvt_pk_bf16_f32 v136, v132, v133
	v_cvt_pk_bf16_f32 v137, v134, v135
	v_lshlrev_b32_e32 v132, 16, v212
	v_and_b32_e32 v133, 0xffff0000, v212
	v_lshlrev_b32_e32 v134, 16, v213
	v_and_b32_e32 v135, 0xffff0000, v213
	v_rcp_f32_e32 v132, v132
	v_rcp_f32_e32 v133, v133
	v_rcp_f32_e32 v134, v134
	v_rcp_f32_e32 v135, v135
	v_pk_mul_f32 v[132:133], v[28:29], v[132:133]
	v_pk_mul_f32 v[134:135], v[30:31], v[134:135]
	v_cvt_pk_bf16_f32 v138, v132, v133
	v_cvt_pk_bf16_f32 v139, v134, v135
	global_store_dwordx4 v[2:3], v[136:139], off offset:256 sc1
	v_lshl_add_u64 v[2:3], v[2:3], 0, s[62:63]
	s_waitcnt vmcnt(15)
	v_lshlrev_b32_e32 v132, 16, v214
	v_and_b32_e32 v133, 0xffff0000, v214
	v_lshlrev_b32_e32 v134, 16, v215
	v_and_b32_e32 v135, 0xffff0000, v215
	v_rcp_f32_e32 v132, v132
	v_rcp_f32_e32 v133, v133
	v_rcp_f32_e32 v134, v134
	v_rcp_f32_e32 v135, v135
	v_pk_mul_f32 v[132:133], v[56:57], v[132:133]
	v_pk_mul_f32 v[134:135], v[58:59], v[134:135]
	v_cvt_pk_bf16_f32 v136, v132, v133
	v_cvt_pk_bf16_f32 v137, v134, v135
	v_lshlrev_b32_e32 v132, 16, v216
	v_and_b32_e32 v133, 0xffff0000, v216
	v_lshlrev_b32_e32 v134, 16, v217
	v_and_b32_e32 v135, 0xffff0000, v217
	v_rcp_f32_e32 v132, v132
	v_rcp_f32_e32 v133, v133
	v_rcp_f32_e32 v134, v134
	v_rcp_f32_e32 v135, v135
	v_pk_mul_f32 v[132:133], v[52:53], v[132:133]
	v_pk_mul_f32 v[134:135], v[54:55], v[134:135]
	v_cvt_pk_bf16_f32 v138, v132, v133
	v_cvt_pk_bf16_f32 v139, v134, v135
	global_store_dwordx4 v[2:3], v[136:139], off sc1
	s_waitcnt vmcnt(15)
	v_lshlrev_b32_e32 v132, 16, v218
	v_and_b32_e32 v133, 0xffff0000, v218
	v_lshlrev_b32_e32 v134, 16, v219
	v_and_b32_e32 v135, 0xffff0000, v219
	v_rcp_f32_e32 v132, v132
	v_rcp_f32_e32 v133, v133
	v_rcp_f32_e32 v134, v134
	v_rcp_f32_e32 v135, v135
	v_pk_mul_f32 v[132:133], v[24:25], v[132:133]
	v_pk_mul_f32 v[134:135], v[26:27], v[134:135]
	v_cvt_pk_bf16_f32 v136, v132, v133
	v_cvt_pk_bf16_f32 v137, v134, v135
	v_lshlrev_b32_e32 v132, 16, v220
	v_and_b32_e32 v133, 0xffff0000, v220
	v_lshlrev_b32_e32 v134, 16, v221
	v_and_b32_e32 v135, 0xffff0000, v221
	v_rcp_f32_e32 v132, v132
	v_rcp_f32_e32 v133, v133
	v_rcp_f32_e32 v134, v134
	v_rcp_f32_e32 v135, v135
	v_pk_mul_f32 v[132:133], v[20:21], v[132:133]
	v_pk_mul_f32 v[134:135], v[22:23], v[134:135]
	v_cvt_pk_bf16_f32 v138, v132, v133
	v_cvt_pk_bf16_f32 v139, v134, v135
	global_store_dwordx4 v[2:3], v[136:139], off offset:256 sc1
	v_lshl_add_u64 v[2:3], v[2:3], 0, s[62:63]
	s_waitcnt vmcnt(15)
	v_lshlrev_b32_e32 v132, 16, v154
	v_and_b32_e32 v133, 0xffff0000, v154
	v_lshlrev_b32_e32 v134, 16, v155
	v_and_b32_e32 v135, 0xffff0000, v155
	v_rcp_f32_e32 v132, v132
	v_rcp_f32_e32 v133, v133
	v_rcp_f32_e32 v134, v134
	v_rcp_f32_e32 v135, v135
	v_pk_mul_f32 v[132:133], v[48:49], v[132:133]
	v_pk_mul_f32 v[134:135], v[50:51], v[134:135]
	v_cvt_pk_bf16_f32 v136, v132, v133
	v_cvt_pk_bf16_f32 v137, v134, v135
	v_lshlrev_b32_e32 v132, 16, v156
	v_and_b32_e32 v133, 0xffff0000, v156
	v_lshlrev_b32_e32 v134, 16, v157
	v_and_b32_e32 v135, 0xffff0000, v157
	v_rcp_f32_e32 v132, v132
	v_rcp_f32_e32 v133, v133
	v_rcp_f32_e32 v134, v134
	v_rcp_f32_e32 v135, v135
	v_pk_mul_f32 v[132:133], v[44:45], v[132:133]
	v_pk_mul_f32 v[134:135], v[46:47], v[134:135]
	v_cvt_pk_bf16_f32 v138, v132, v133
	v_cvt_pk_bf16_f32 v139, v134, v135
	global_store_dwordx4 v[2:3], v[136:139], off sc1
	s_waitcnt vmcnt(15)
	v_lshlrev_b32_e32 v132, 16, v232
	v_and_b32_e32 v133, 0xffff0000, v232
	v_lshlrev_b32_e32 v134, 16, v233
	v_and_b32_e32 v135, 0xffff0000, v233
	v_rcp_f32_e32 v132, v132
	v_rcp_f32_e32 v133, v133
	v_rcp_f32_e32 v134, v134
	v_rcp_f32_e32 v135, v135
	v_pk_mul_f32 v[132:133], v[16:17], v[132:133]
	v_pk_mul_f32 v[134:135], v[18:19], v[134:135]
	v_cvt_pk_bf16_f32 v136, v132, v133
	v_cvt_pk_bf16_f32 v137, v134, v135
	v_lshlrev_b32_e32 v132, 16, v234
	v_and_b32_e32 v133, 0xffff0000, v234
	v_lshlrev_b32_e32 v134, 16, v235
	v_and_b32_e32 v135, 0xffff0000, v235
	v_rcp_f32_e32 v132, v132
	v_rcp_f32_e32 v133, v133
	v_rcp_f32_e32 v134, v134
	v_rcp_f32_e32 v135, v135
	v_pk_mul_f32 v[132:133], v[12:13], v[132:133]
	v_pk_mul_f32 v[134:135], v[14:15], v[134:135]
	v_cvt_pk_bf16_f32 v138, v132, v133
	v_cvt_pk_bf16_f32 v139, v134, v135
	global_store_dwordx4 v[2:3], v[136:139], off offset:256 sc1
	v_lshl_add_u64 v[2:3], v[2:3], 0, s[62:63]
	s_waitcnt vmcnt(14)
	v_lshlrev_b32_e32 v132, 16, v164
	v_and_b32_e32 v133, 0xffff0000, v164
	v_lshlrev_b32_e32 v134, 16, v165
	v_and_b32_e32 v135, 0xffff0000, v165
	v_rcp_f32_e32 v132, v132
	v_rcp_f32_e32 v133, v133
	v_rcp_f32_e32 v134, v134
	v_rcp_f32_e32 v135, v135
	v_pk_mul_f32 v[132:133], v[40:41], v[132:133]
	v_pk_mul_f32 v[134:135], v[42:43], v[134:135]
	v_cvt_pk_bf16_f32 v136, v132, v133
	v_cvt_pk_bf16_f32 v137, v134, v135
	v_lshlrev_b32_e32 v132, 16, v166
	v_and_b32_e32 v133, 0xffff0000, v166
	v_lshlrev_b32_e32 v134, 16, v167
	v_and_b32_e32 v135, 0xffff0000, v167
	v_rcp_f32_e32 v132, v132
	v_rcp_f32_e32 v133, v133
	v_rcp_f32_e32 v134, v134
	v_rcp_f32_e32 v135, v135
	v_pk_mul_f32 v[132:133], v[36:37], v[132:133]
	v_pk_mul_f32 v[134:135], v[38:39], v[134:135]
	v_cvt_pk_bf16_f32 v138, v132, v133
	v_cvt_pk_bf16_f32 v139, v134, v135
	global_store_dwordx4 v[2:3], v[136:139], off sc1
	s_waitcnt vmcnt(13)
	v_lshlrev_b32_e32 v132, 16, v168
	v_and_b32_e32 v133, 0xffff0000, v168
	v_lshlrev_b32_e32 v134, 16, v169
	v_and_b32_e32 v135, 0xffff0000, v169
	v_rcp_f32_e32 v132, v132
	v_rcp_f32_e32 v133, v133
	v_rcp_f32_e32 v134, v134
	v_rcp_f32_e32 v135, v135
	v_pk_mul_f32 v[132:133], v[8:9], v[132:133]
	v_pk_mul_f32 v[134:135], v[10:11], v[134:135]
	v_cvt_pk_bf16_f32 v136, v132, v133
	v_cvt_pk_bf16_f32 v137, v134, v135
	v_lshlrev_b32_e32 v132, 16, v170
	v_and_b32_e32 v133, 0xffff0000, v170
	v_lshlrev_b32_e32 v134, 16, v171
	v_and_b32_e32 v135, 0xffff0000, v171
	v_rcp_f32_e32 v132, v132
	v_rcp_f32_e32 v133, v133
	v_rcp_f32_e32 v134, v134
	v_rcp_f32_e32 v135, v135
	v_pk_mul_f32 v[132:133], v[4:5], v[132:133]
	v_pk_mul_f32 v[134:135], v[6:7], v[134:135]
	v_cvt_pk_bf16_f32 v138, v132, v133
	v_cvt_pk_bf16_f32 v139, v134, v135
	global_store_dwordx4 v[2:3], v[136:139], off offset:256 sc1
	s_cbranch_execz .LBB0_623

.LBB0_623:
	s_lshl_b32 s62, s73, 2
	s_add_i32 s62, s62, s74
	s_add_i32 s62, s62, s47
	s_ashr_i32 s63, s62, 31
	s_lshl_b64 s[64:65], s[62:63], 17
	s_add_i32 s62, s62, 4
	s_ashr_i32 s63, s62, 31
	s_lshl_b64 s[62:63], s[62:63], 17
	s_add_u32 s64, s64, 0x1000
	s_addc_u32 s65, s65, 0
	s_add_u32 s62, s62, 0x1000
	s_addc_u32 s63, s63, 0
	v_lshl_add_u64 v[2:3], v[148:149], 0, s[64:65]
	v_lshl_add_u64 v[158:159], v[148:149], 0, s[62:63]
	s_mov_b64 s[62:63], 0x2000
	s_movk_i32 s91, 0x1000
	global_load_dwordx4 v[164:167], v[2:3], off offset:-4096
	global_load_dwordx4 v[168:171], v[158:159], off offset:-4096
	global_load_dwordx4 v[172:175], v[2:3], off offset:-3072
	global_load_dwordx4 v[176:179], v[158:159], off offset:-3072
	global_load_dwordx4 v[180:183], v[2:3], off offset:-2048
	global_load_dwordx4 v[184:187], v[158:159], off offset:-2048
	global_load_dwordx4 v[188:191], v[2:3], off offset:-1024
	global_load_dwordx4 v[192:195], v[158:159], off offset:-1024
	global_load_dwordx4 v[206:209], v[2:3], off
	global_load_dwordx4 v[210:213], v[158:159], off
	global_load_dwordx4 v[214:217], v[2:3], off offset:1024
	global_load_dwordx4 v[218:221], v[158:159], off offset:1024
	global_load_dwordx4 v[154:157], v[2:3], off offset:2048
	global_load_dwordx4 v[232:235], v[158:159], off offset:2048
	s_waitcnt vmcnt(12)
	v_lshlrev_b32_e32 v132, 16, v164
	v_and_b32_e32 v133, 0xffff0000, v164
	v_lshlrev_b32_e32 v136, 16, v165
	v_and_b32_e32 v137, 0xffff0000, v165
	v_rcp_f32_e32 v132, v132
	v_rcp_f32_e32 v133, v133
	v_rcp_f32_e32 v136, v136
	v_rcp_f32_e32 v137, v137
	v_lshlrev_b32_e32 v134, 16, v168
	v_and_b32_e32 v135, 0xffff0000, v168
	v_lshlrev_b32_e32 v138, 16, v169
	v_and_b32_e32 v139, 0xffff0000, v169
	v_pk_mul_f32 v[132:133], v[132:133], v[134:135]
	v_pk_mul_f32 v[136:137], v[136:137], v[138:139]
	v_pk_mul_f32 v[128:129], v[128:129], v[132:133]
	v_pk_mul_f32 v[130:131], v[130:131], v[136:137]
	v_lshlrev_b32_e32 v132, 16, v166
	v_and_b32_e32 v133, 0xffff0000, v166
	v_lshlrev_b32_e32 v136, 16, v167
	v_and_b32_e32 v137, 0xffff0000, v167
	v_rcp_f32_e32 v132, v132
	v_rcp_f32_e32 v133, v133
	v_rcp_f32_e32 v136, v136
	v_rcp_f32_e32 v137, v137
	v_lshlrev_b32_e32 v134, 16, v170
	v_and_b32_e32 v135, 0xffff0000, v170
	v_lshlrev_b32_e32 v138, 16, v171
	v_and_b32_e32 v139, 0xffff0000, v171
	v_pk_mul_f32 v[132:133], v[132:133], v[134:135]
	v_pk_mul_f32 v[136:137], v[136:137], v[138:139]
	v_pk_mul_f32 v[124:125], v[124:125], v[132:133]
	v_pk_mul_f32 v[126:127], v[126:127], v[136:137]
	global_load_dwordx4 v[164:167], v[2:3], off offset:3072
	global_load_dwordx4 v[168:171], v[158:159], off offset:3072
	v_lshl_add_u64 v[2:3], v[2:3], 0, s[62:63]
	v_lshl_add_u64 v[158:159], v[158:159], 0, s[62:63]
	s_waitcnt vmcnt(12)
	v_lshlrev_b32_e32 v132, 16, v172
	v_and_b32_e32 v133, 0xffff0000, v172
	v_lshlrev_b32_e32 v136, 16, v173
	v_and_b32_e32 v137, 0xffff0000, v173
	v_rcp_f32_e32 v132, v132
	v_rcp_f32_e32 v133, v133
	v_rcp_f32_e32 v136, v136
	v_rcp_f32_e32 v137, v137
	v_lshlrev_b32_e32 v134, 16, v176
	v_and_b32_e32 v135, 0xffff0000, v176
	v_lshlrev_b32_e32 v138, 16, v177
	v_and_b32_e32 v139, 0xffff0000, v177
	v_pk_mul_f32 v[132:133], v[132:133], v[134:135]
	v_pk_mul_f32 v[136:137], v[136:137], v[138:139]
	v_pk_mul_f32 v[96:97], v[96:97], v[132:133]
	v_pk_mul_f32 v[98:99], v[98:99], v[136:137]
	v_lshlrev_b32_e32 v132, 16, v174
	v_and_b32_e32 v133, 0xffff0000, v174
	v_lshlrev_b32_e32 v136, 16, v175
	v_and_b32_e32 v137, 0xffff0000, v175
	v_rcp_f32_e32 v132, v132
	v_rcp_f32_e32 v133, v133
	v_rcp_f32_e32 v136, v136
	v_rcp_f32_e32 v137, v137
	v_lshlrev_b32_e32 v134, 16, v178
	v_and_b32_e32 v135, 0xffff0000, v178
	v_lshlrev_b32_e32 v138, 16, v179
	v_and_b32_e32 v139, 0xffff0000, v179
	v_pk_mul_f32 v[132:133], v[132:133], v[134:135]
	v_pk_mul_f32 v[136:137], v[136:137], v[138:139]
	v_pk_mul_f32 v[92:93], v[92:93], v[132:133]
	v_pk_mul_f32 v[94:95], v[94:95], v[136:137]
	global_load_dwordx4 v[172:175], v[2:3], off offset:-4096
	global_load_dwordx4 v[176:179], v[158:159], off offset:-4096
	s_waitcnt vmcnt(12)
	v_lshlrev_b32_e32 v132, 16, v180
	v_and_b32_e32 v133, 0xffff0000, v180
	v_lshlrev_b32_e32 v136, 16, v181
	v_and_b32_e32 v137, 0xffff0000, v181
	v_rcp_f32_e32 v132, v132
	v_rcp_f32_e32 v133, v133
	v_rcp_f32_e32 v136, v136
	v_rcp_f32_e32 v137, v137
	v_lshlrev_b32_e32 v134, 16, v184
	v_and_b32_e32 v135, 0xffff0000, v184
	v_lshlrev_b32_e32 v138, 16, v185
	v_and_b32_e32 v139, 0xffff0000, v185
	v_pk_mul_f32 v[132:133], v[132:133], v[134:135]
	v_pk_mul_f32 v[136:137], v[136:137], v[138:139]
	v_pk_mul_f32 v[120:121], v[120:121], v[132:133]
	v_pk_mul_f32 v[122:123], v[122:123], v[136:137]
	v_lshlrev_b32_e32 v132, 16, v182
	v_and_b32_e32 v133, 0xffff0000, v182
	v_lshlrev_b32_e32 v136, 16, v183
	v_and_b32_e32 v137, 0xffff0000, v183
	v_rcp_f32_e32 v132, v132
	v_rcp_f32_e32 v133, v133
	v_rcp_f32_e32 v136, v136
	v_rcp_f32_e32 v137, v137
	v_lshlrev_b32_e32 v134, 16, v186
	v_and_b32_e32 v135, 0xffff0000, v186
	v_lshlrev_b32_e32 v138, 16, v187
	v_and_b32_e32 v139, 0xffff0000, v187
	v_pk_mul_f32 v[132:133], v[132:133], v[134:135]
	v_pk_mul_f32 v[136:137], v[136:137], v[138:139]
	v_pk_mul_f32 v[116:117], v[116:117], v[132:133]
	v_pk_mul_f32 v[118:119], v[118:119], v[136:137]
	global_load_dwordx4 v[180:183], v[2:3], off offset:-3072
	global_load_dwordx4 v[184:187], v[158:159], off offset:-3072
	s_waitcnt vmcnt(12)
	v_lshlrev_b32_e32 v132, 16, v188
	v_and_b32_e32 v133, 0xffff0000, v188
	v_lshlrev_b32_e32 v136, 16, v189
	v_and_b32_e32 v137, 0xffff0000, v189
	v_rcp_f32_e32 v132, v132
	v_rcp_f32_e32 v133, v133
	v_rcp_f32_e32 v136, v136
	v_rcp_f32_e32 v137, v137
	v_lshlrev_b32_e32 v134, 16, v192
	v_and_b32_e32 v135, 0xffff0000, v192
	v_lshlrev_b32_e32 v138, 16, v193
	v_and_b32_e32 v139, 0xffff0000, v193
	v_pk_mul_f32 v[132:133], v[132:133], v[134:135]
	v_pk_mul_f32 v[136:137], v[136:137], v[138:139]
	v_pk_mul_f32 v[88:89], v[88:89], v[132:133]
	v_pk_mul_f32 v[90:91], v[90:91], v[136:137]
	v_lshlrev_b32_e32 v132, 16, v190
	v_and_b32_e32 v133, 0xffff0000, v190
	v_lshlrev_b32_e32 v136, 16, v191
	v_and_b32_e32 v137, 0xffff0000, v191
	v_rcp_f32_e32 v132, v132
	v_rcp_f32_e32 v133, v133
	v_rcp_f32_e32 v136, v136
	v_rcp_f32_e32 v137, v137
	v_lshlrev_b32_e32 v134, 16, v194
	v_and_b32_e32 v135, 0xffff0000, v194
	v_lshlrev_b32_e32 v138, 16, v195
	v_and_b32_e32 v139, 0xffff0000, v195
	v_pk_mul_f32 v[132:133], v[132:133], v[134:135]
	v_pk_mul_f32 v[136:137], v[136:137], v[138:139]
	v_pk_mul_f32 v[84:85], v[84:85], v[132:133]
	v_pk_mul_f32 v[86:87], v[86:87], v[136:137]
	global_load_dwordx4 v[188:191], v[2:3], off offset:-2048
	global_load_dwordx4 v[192:195], v[158:159], off offset:-2048
	s_waitcnt vmcnt(12)
	v_lshlrev_b32_e32 v132, 16, v206
	v_and_b32_e32 v133, 0xffff0000, v206
	v_lshlrev_b32_e32 v136, 16, v207
	v_and_b32_e32 v137, 0xffff0000, v207
	v_rcp_f32_e32 v132, v132
	v_rcp_f32_e32 v133, v133
	v_rcp_f32_e32 v136, v136
	v_rcp_f32_e32 v137, v137
	v_lshlrev_b32_e32 v134, 16, v210
	v_and_b32_e32 v135, 0xffff0000, v210
	v_lshlrev_b32_e32 v138, 16, v211
	v_and_b32_e32 v139, 0xffff0000, v211
	v_pk_mul_f32 v[132:133], v[132:133], v[134:135]
	v_pk_mul_f32 v[136:137], v[136:137], v[138:139]
	v_pk_mul_f32 v[112:113], v[112:113], v[132:133]
	v_pk_mul_f32 v[114:115], v[114:115], v[136:137]
	v_lshlrev_b32_e32 v132, 16, v208
	v_and_b32_e32 v133, 0xffff0000, v208
	v_lshlrev_b32_e32 v136, 16, v209
	v_and_b32_e32 v137, 0xffff0000, v209
	v_rcp_f32_e32 v132, v132
	v_rcp_f32_e32 v133, v133
	v_rcp_f32_e32 v136, v136
	v_rcp_f32_e32 v137, v137
	v_lshlrev_b32_e32 v134, 16, v212
	v_and_b32_e32 v135, 0xffff0000, v212
	v_lshlrev_b32_e32 v138, 16, v213
	v_and_b32_e32 v139, 0xffff0000, v213
	v_pk_mul_f32 v[132:133], v[132:133], v[134:135]
	v_pk_mul_f32 v[136:137], v[136:137], v[138:139]
	v_pk_mul_f32 v[108:109], v[108:109], v[132:133]
	v_pk_mul_f32 v[110:111], v[110:111], v[136:137]
	global_load_dwordx4 v[206:209], v[2:3], off offset:-1024
	global_load_dwordx4 v[210:213], v[158:159], off offset:-1024
	s_waitcnt vmcnt(12)
	v_lshlrev_b32_e32 v132, 16, v214
	v_and_b32_e32 v133, 0xffff0000, v214
	v_lshlrev_b32_e32 v136, 16, v215
	v_and_b32_e32 v137, 0xffff0000, v215
	v_rcp_f32_e32 v132, v132
	v_rcp_f32_e32 v133, v133
	v_rcp_f32_e32 v136, v136
	v_rcp_f32_e32 v137, v137
	v_lshlrev_b32_e32 v134, 16, v218
	v_and_b32_e32 v135, 0xffff0000, v218
	v_lshlrev_b32_e32 v138, 16, v219
	v_and_b32_e32 v139, 0xffff0000, v219
	v_pk_mul_f32 v[132:133], v[132:133], v[134:135]
	v_pk_mul_f32 v[136:137], v[136:137], v[138:139]
	v_pk_mul_f32 v[80:81], v[80:81], v[132:133]
	v_pk_mul_f32 v[82:83], v[82:83], v[136:137]
	v_lshlrev_b32_e32 v132, 16, v216
	v_and_b32_e32 v133, 0xffff0000, v216
	v_lshlrev_b32_e32 v136, 16, v217
	v_and_b32_e32 v137, 0xffff0000, v217
	v_rcp_f32_e32 v132, v132
	v_rcp_f32_e32 v133, v133
	v_rcp_f32_e32 v136, v136
	v_rcp_f32_e32 v137, v137
	v_lshlrev_b32_e32 v134, 16, v220
	v_and_b32_e32 v135, 0xffff0000, v220
	v_lshlrev_b32_e32 v138, 16, v221
	v_and_b32_e32 v139, 0xffff0000, v221
	v_pk_mul_f32 v[132:133], v[132:133], v[134:135]
	v_pk_mul_f32 v[136:137], v[136:137], v[138:139]
	v_pk_mul_f32 v[76:77], v[76:77], v[132:133]
	v_pk_mul_f32 v[78:79], v[78:79], v[136:137]
	global_load_dwordx4 v[214:217], v[2:3], off
	global_load_dwordx4 v[218:221], v[158:159], off
	s_waitcnt vmcnt(12)
	v_lshlrev_b32_e32 v132, 16, v154
	v_and_b32_e32 v133, 0xffff0000, v154
	v_lshlrev_b32_e32 v136, 16, v155
	v_and_b32_e32 v137, 0xffff0000, v155
	v_rcp_f32_e32 v132, v132
	v_rcp_f32_e32 v133, v133
	v_rcp_f32_e32 v136, v136
	v_rcp_f32_e32 v137, v137
	v_lshlrev_b32_e32 v134, 16, v232
	v_and_b32_e32 v135, 0xffff0000, v232
	v_lshlrev_b32_e32 v138, 16, v233
	v_and_b32_e32 v139, 0xffff0000, v233
	v_pk_mul_f32 v[132:133], v[132:133], v[134:135]
	v_pk_mul_f32 v[136:137], v[136:137], v[138:139]
	v_pk_mul_f32 v[104:105], v[104:105], v[132:133]
	v_pk_mul_f32 v[106:107], v[106:107], v[136:137]
	v_lshlrev_b32_e32 v132, 16, v156
	v_and_b32_e32 v133, 0xffff0000, v156
	v_lshlrev_b32_e32 v136, 16, v157
	v_and_b32_e32 v137, 0xffff0000, v157
	v_rcp_f32_e32 v132, v132
	v_rcp_f32_e32 v133, v133
	v_rcp_f32_e32 v136, v136
	v_rcp_f32_e32 v137, v137
	v_lshlrev_b32_e32 v134, 16, v234
	v_and_b32_e32 v135, 0xffff0000, v234
	v_lshlrev_b32_e32 v138, 16, v235
	v_and_b32_e32 v139, 0xffff0000, v235
	v_pk_mul_f32 v[132:133], v[132:133], v[134:135]
	v_pk_mul_f32 v[136:137], v[136:137], v[138:139]
	v_pk_mul_f32 v[100:101], v[100:101], v[132:133]
	v_pk_mul_f32 v[102:103], v[102:103], v[136:137]
	global_load_dwordx4 v[154:157], v[2:3], off offset:1024
	global_load_dwordx4 v[232:235], v[158:159], off offset:1024
	s_waitcnt vmcnt(12)
	v_lshlrev_b32_e32 v132, 16, v164
	v_and_b32_e32 v133, 0xffff0000, v164
	v_lshlrev_b32_e32 v136, 16, v165
	v_and_b32_e32 v137, 0xffff0000, v165
	v_rcp_f32_e32 v132, v132
	v_rcp_f32_e32 v133, v133
	v_rcp_f32_e32 v136, v136
	v_rcp_f32_e32 v137, v137
	v_lshlrev_b32_e32 v134, 16, v168
	v_and_b32_e32 v135, 0xffff0000, v168
	v_lshlrev_b32_e32 v138, 16, v169
	v_and_b32_e32 v139, 0xffff0000, v169
	v_pk_mul_f32 v[132:133], v[132:133], v[134:135]
	v_pk_mul_f32 v[136:137], v[136:137], v[138:139]
	v_pk_mul_f32 v[72:73], v[72:73], v[132:133]
	v_pk_mul_f32 v[74:75], v[74:75], v[136:137]
	v_lshlrev_b32_e32 v132, 16, v166
	v_and_b32_e32 v133, 0xffff0000, v166
	v_lshlrev_b32_e32 v136, 16, v167
	v_and_b32_e32 v137, 0xffff0000, v167
	v_rcp_f32_e32 v132, v132
	v_rcp_f32_e32 v133, v133
	v_rcp_f32_e32 v136, v136
	v_rcp_f32_e32 v137, v137
	v_lshlrev_b32_e32 v134, 16, v170
	v_and_b32_e32 v135, 0xffff0000, v170
	v_lshlrev_b32_e32 v138, 16, v171
	v_and_b32_e32 v139, 0xffff0000, v171
	v_pk_mul_f32 v[132:133], v[132:133], v[134:135]
	v_pk_mul_f32 v[136:137], v[136:137], v[138:139]
	v_pk_mul_f32 v[68:69], v[68:69], v[132:133]
	v_pk_mul_f32 v[70:71], v[70:71], v[136:137]
	global_load_dwordx4 v[164:167], v[2:3], off offset:2048
	global_load_dwordx4 v[168:171], v[158:159], off offset:2048
	s_waitcnt vmcnt(12)
	v_lshlrev_b32_e32 v132, 16, v172
	v_and_b32_e32 v133, 0xffff0000, v172
	v_lshlrev_b32_e32 v136, 16, v173
	v_and_b32_e32 v137, 0xffff0000, v173
	v_rcp_f32_e32 v132, v132
	v_rcp_f32_e32 v133, v133
	v_rcp_f32_e32 v136, v136
	v_rcp_f32_e32 v137, v137
	v_lshlrev_b32_e32 v134, 16, v176
	v_and_b32_e32 v135, 0xffff0000, v176
	v_lshlrev_b32_e32 v138, 16, v177
	v_and_b32_e32 v139, 0xffff0000, v177
	v_pk_mul_f32 v[132:133], v[132:133], v[134:135]
	v_pk_mul_f32 v[136:137], v[136:137], v[138:139]
	v_pk_mul_f32 v[64:65], v[64:65], v[132:133]
	v_pk_mul_f32 v[66:67], v[66:67], v[136:137]
	v_lshlrev_b32_e32 v132, 16, v174
	v_and_b32_e32 v133, 0xffff0000, v174
	v_lshlrev_b32_e32 v136, 16, v175
	v_and_b32_e32 v137, 0xffff0000, v175
	v_rcp_f32_e32 v132, v132
	v_rcp_f32_e32 v133, v133
	v_rcp_f32_e32 v136, v136
	v_rcp_f32_e32 v137, v137
	v_lshlrev_b32_e32 v134, 16, v178
	v_and_b32_e32 v135, 0xffff0000, v178
	v_lshlrev_b32_e32 v138, 16, v179
	v_and_b32_e32 v139, 0xffff0000, v179
	v_pk_mul_f32 v[132:133], v[132:133], v[134:135]
	v_pk_mul_f32 v[136:137], v[136:137], v[138:139]
	v_pk_mul_f32 v[60:61], v[60:61], v[132:133]
	v_pk_mul_f32 v[62:63], v[62:63], v[136:137]
	global_load_dwordx4 v[172:175], v[2:3], off offset:3072
	global_load_dwordx4 v[176:179], v[158:159], off offset:3072
	s_waitcnt vmcnt(12)
	v_lshlrev_b32_e32 v132, 16, v180
	v_and_b32_e32 v133, 0xffff0000, v180
	v_lshlrev_b32_e32 v136, 16, v181
	v_and_b32_e32 v137, 0xffff0000, v181
	v_rcp_f32_e32 v132, v132
	v_rcp_f32_e32 v133, v133
	v_rcp_f32_e32 v136, v136
	v_rcp_f32_e32 v137, v137
	v_lshlrev_b32_e32 v134, 16, v184
	v_and_b32_e32 v135, 0xffff0000, v184
	v_lshlrev_b32_e32 v138, 16, v185
	v_and_b32_e32 v139, 0xffff0000, v185
	v_pk_mul_f32 v[132:133], v[132:133], v[134:135]
	v_pk_mul_f32 v[136:137], v[136:137], v[138:139]
	v_pk_mul_f32 v[32:33], v[32:33], v[132:133]
	v_pk_mul_f32 v[34:35], v[34:35], v[136:137]
	v_lshlrev_b32_e32 v132, 16, v182
	v_and_b32_e32 v133, 0xffff0000, v182
	v_lshlrev_b32_e32 v136, 16, v183
	v_and_b32_e32 v137, 0xffff0000, v183
	v_rcp_f32_e32 v132, v132
	v_rcp_f32_e32 v133, v133
	v_rcp_f32_e32 v136, v136
	v_rcp_f32_e32 v137, v137
	v_lshlrev_b32_e32 v134, 16, v186
	v_and_b32_e32 v135, 0xffff0000, v186
	v_lshlrev_b32_e32 v138, 16, v187
	v_and_b32_e32 v139, 0xffff0000, v187
	v_pk_mul_f32 v[132:133], v[132:133], v[134:135]
	v_pk_mul_f32 v[136:137], v[136:137], v[138:139]
	v_pk_mul_f32 v[28:29], v[28:29], v[132:133]
	v_pk_mul_f32 v[30:31], v[30:31], v[136:137]
	s_waitcnt vmcnt(10)
	v_lshlrev_b32_e32 v132, 16, v188
	v_and_b32_e32 v133, 0xffff0000, v188
	v_lshlrev_b32_e32 v136, 16, v189
	v_and_b32_e32 v137, 0xffff0000, v189
	v_rcp_f32_e32 v132, v132
	v_rcp_f32_e32 v133, v133
	v_rcp_f32_e32 v136, v136
	v_rcp_f32_e32 v137, v137
	v_lshlrev_b32_e32 v134, 16, v192
	v_and_b32_e32 v135, 0xffff0000, v192
	v_lshlrev_b32_e32 v138, 16, v193
	v_and_b32_e32 v139, 0xffff0000, v193
	v_pk_mul_f32 v[132:133], v[132:133], v[134:135]
	v_pk_mul_f32 v[136:137], v[136:137], v[138:139]
	v_pk_mul_f32 v[56:57], v[56:57], v[132:133]
	v_pk_mul_f32 v[58:59], v[58:59], v[136:137]
	v_lshlrev_b32_e32 v132, 16, v190
	v_and_b32_e32 v133, 0xffff0000, v190
	v_lshlrev_b32_e32 v136, 16, v191
	v_and_b32_e32 v137, 0xffff0000, v191
	v_rcp_f32_e32 v132, v132
	v_rcp_f32_e32 v133, v133
	v_rcp_f32_e32 v136, v136
	v_rcp_f32_e32 v137, v137
	v_lshlrev_b32_e32 v134, 16, v194
	v_and_b32_e32 v135, 0xffff0000, v194
	v_lshlrev_b32_e32 v138, 16, v195
	v_and_b32_e32 v139, 0xffff0000, v195
	v_pk_mul_f32 v[132:133], v[132:133], v[134:135]
	v_pk_mul_f32 v[136:137], v[136:137], v[138:139]
	v_pk_mul_f32 v[52:53], v[52:53], v[132:133]
	v_pk_mul_f32 v[54:55], v[54:55], v[136:137]
	s_waitcnt vmcnt(8)
	v_lshlrev_b32_e32 v132, 16, v206
	v_and_b32_e32 v133, 0xffff0000, v206
	v_lshlrev_b32_e32 v136, 16, v207
	v_and_b32_e32 v137, 0xffff0000, v207
	v_rcp_f32_e32 v132, v132
	v_rcp_f32_e32 v133, v133
	v_rcp_f32_e32 v136, v136
	v_rcp_f32_e32 v137, v137
	v_lshlrev_b32_e32 v134, 16, v210
	v_and_b32_e32 v135, 0xffff0000, v210
	v_lshlrev_b32_e32 v138, 16, v211
	v_and_b32_e32 v139, 0xffff0000, v211
	v_pk_mul_f32 v[132:133], v[132:133], v[134:135]
	v_pk_mul_f32 v[136:137], v[136:137], v[138:139]
	v_pk_mul_f32 v[24:25], v[24:25], v[132:133]
	v_pk_mul_f32 v[26:27], v[26:27], v[136:137]
	v_lshlrev_b32_e32 v132, 16, v208
	v_and_b32_e32 v133, 0xffff0000, v208
	v_lshlrev_b32_e32 v136, 16, v209
	v_and_b32_e32 v137, 0xffff0000, v209
	v_rcp_f32_e32 v132, v132
	v_rcp_f32_e32 v133, v133
	v_rcp_f32_e32 v136, v136
	v_rcp_f32_e32 v137, v137
	v_lshlrev_b32_e32 v134, 16, v212
	v_and_b32_e32 v135, 0xffff0000, v212
	v_lshlrev_b32_e32 v138, 16, v213
	v_and_b32_e32 v139, 0xffff0000, v213
	v_pk_mul_f32 v[132:133], v[132:133], v[134:135]
	v_pk_mul_f32 v[136:137], v[136:137], v[138:139]
	v_pk_mul_f32 v[20:21], v[20:21], v[132:133]
	v_pk_mul_f32 v[22:23], v[22:23], v[136:137]
	s_waitcnt vmcnt(6)
	v_lshlrev_b32_e32 v132, 16, v214
	v_and_b32_e32 v133, 0xffff0000, v214
	v_lshlrev_b32_e32 v136, 16, v215
	v_and_b32_e32 v137, 0xffff0000, v215
	v_rcp_f32_e32 v132, v132
	v_rcp_f32_e32 v133, v133
	v_rcp_f32_e32 v136, v136
	v_rcp_f32_e32 v137, v137
	v_lshlrev_b32_e32 v134, 16, v218
	v_and_b32_e32 v135, 0xffff0000, v218
	v_lshlrev_b32_e32 v138, 16, v219
	v_and_b32_e32 v139, 0xffff0000, v219
	v_pk_mul_f32 v[132:133], v[132:133], v[134:135]
	v_pk_mul_f32 v[136:137], v[136:137], v[138:139]
	v_pk_mul_f32 v[48:49], v[48:49], v[132:133]
	v_pk_mul_f32 v[50:51], v[50:51], v[136:137]
	v_lshlrev_b32_e32 v132, 16, v216
	v_and_b32_e32 v133, 0xffff0000, v216
	v_lshlrev_b32_e32 v136, 16, v217
	v_and_b32_e32 v137, 0xffff0000, v217
	v_rcp_f32_e32 v132, v132
	v_rcp_f32_e32 v133, v133
	v_rcp_f32_e32 v136, v136
	v_rcp_f32_e32 v137, v137
	v_lshlrev_b32_e32 v134, 16, v220
	v_and_b32_e32 v135, 0xffff0000, v220
	v_lshlrev_b32_e32 v138, 16, v221
	v_and_b32_e32 v139, 0xffff0000, v221
	v_pk_mul_f32 v[132:133], v[132:133], v[134:135]
	v_pk_mul_f32 v[136:137], v[136:137], v[138:139]
	v_pk_mul_f32 v[44:45], v[44:45], v[132:133]
	v_pk_mul_f32 v[46:47], v[46:47], v[136:137]
	s_waitcnt vmcnt(4)
	v_lshlrev_b32_e32 v132, 16, v154
	v_and_b32_e32 v133, 0xffff0000, v154
	v_lshlrev_b32_e32 v136, 16, v155
	v_and_b32_e32 v137, 0xffff0000, v155
	v_rcp_f32_e32 v132, v132
	v_rcp_f32_e32 v133, v133
	v_rcp_f32_e32 v136, v136
	v_rcp_f32_e32 v137, v137
	v_lshlrev_b32_e32 v134, 16, v232
	v_and_b32_e32 v135, 0xffff0000, v232
	v_lshlrev_b32_e32 v138, 16, v233
	v_and_b32_e32 v139, 0xffff0000, v233
	v_pk_mul_f32 v[132:133], v[132:133], v[134:135]
	v_pk_mul_f32 v[136:137], v[136:137], v[138:139]
	v_pk_mul_f32 v[16:17], v[16:17], v[132:133]
	v_pk_mul_f32 v[18:19], v[18:19], v[136:137]
	v_lshlrev_b32_e32 v132, 16, v156
	v_and_b32_e32 v133, 0xffff0000, v156
	v_lshlrev_b32_e32 v136, 16, v157
	v_and_b32_e32 v137, 0xffff0000, v157
	v_rcp_f32_e32 v132, v132
	v_rcp_f32_e32 v133, v133
	v_rcp_f32_e32 v136, v136
	v_rcp_f32_e32 v137, v137
	v_lshlrev_b32_e32 v134, 16, v234
	v_and_b32_e32 v135, 0xffff0000, v234
	v_lshlrev_b32_e32 v138, 16, v235
	v_and_b32_e32 v139, 0xffff0000, v235
	v_pk_mul_f32 v[132:133], v[132:133], v[134:135]
	v_pk_mul_f32 v[136:137], v[136:137], v[138:139]
	v_pk_mul_f32 v[12:13], v[12:13], v[132:133]
	v_pk_mul_f32 v[14:15], v[14:15], v[136:137]
	s_waitcnt vmcnt(2)
	v_lshlrev_b32_e32 v132, 16, v164
	v_and_b32_e32 v133, 0xffff0000, v164
	v_lshlrev_b32_e32 v136, 16, v165
	v_and_b32_e32 v137, 0xffff0000, v165
	v_rcp_f32_e32 v132, v132
	v_rcp_f32_e32 v133, v133
	v_rcp_f32_e32 v136, v136
	v_rcp_f32_e32 v137, v137
	v_lshlrev_b32_e32 v134, 16, v168
	v_and_b32_e32 v135, 0xffff0000, v168
	v_lshlrev_b32_e32 v138, 16, v169
	v_and_b32_e32 v139, 0xffff0000, v169
	v_pk_mul_f32 v[132:133], v[132:133], v[134:135]
	v_pk_mul_f32 v[136:137], v[136:137], v[138:139]
	v_pk_mul_f32 v[40:41], v[40:41], v[132:133]
	v_pk_mul_f32 v[42:43], v[42:43], v[136:137]
	v_lshlrev_b32_e32 v132, 16, v166
	v_and_b32_e32 v133, 0xffff0000, v166
	v_lshlrev_b32_e32 v136, 16, v167
	v_and_b32_e32 v137, 0xffff0000, v167
	v_rcp_f32_e32 v132, v132
	v_rcp_f32_e32 v133, v133
	v_rcp_f32_e32 v136, v136
	v_rcp_f32_e32 v137, v137
	v_lshlrev_b32_e32 v134, 16, v170
	v_and_b32_e32 v135, 0xffff0000, v170
	v_lshlrev_b32_e32 v138, 16, v171
	v_and_b32_e32 v139, 0xffff0000, v171
	v_pk_mul_f32 v[132:133], v[132:133], v[134:135]
	v_pk_mul_f32 v[136:137], v[136:137], v[138:139]
	v_pk_mul_f32 v[36:37], v[36:37], v[132:133]
	v_pk_mul_f32 v[38:39], v[38:39], v[136:137]
	s_waitcnt vmcnt(0)
	v_lshlrev_b32_e32 v132, 16, v172
	v_and_b32_e32 v133, 0xffff0000, v172
	v_lshlrev_b32_e32 v136, 16, v173
	v_and_b32_e32 v137, 0xffff0000, v173
	v_rcp_f32_e32 v132, v132
	v_rcp_f32_e32 v133, v133
	v_rcp_f32_e32 v136, v136
	v_rcp_f32_e32 v137, v137
	v_lshlrev_b32_e32 v134, 16, v176
	v_and_b32_e32 v135, 0xffff0000, v176
	v_lshlrev_b32_e32 v138, 16, v177
	v_and_b32_e32 v139, 0xffff0000, v177
	v_pk_mul_f32 v[132:133], v[132:133], v[134:135]
	v_pk_mul_f32 v[136:137], v[136:137], v[138:139]
	v_pk_mul_f32 v[8:9], v[8:9], v[132:133]
	v_pk_mul_f32 v[10:11], v[10:11], v[136:137]
	v_lshlrev_b32_e32 v132, 16, v174
	v_and_b32_e32 v133, 0xffff0000, v174
	v_lshlrev_b32_e32 v136, 16, v175
	v_and_b32_e32 v137, 0xffff0000, v175
	v_rcp_f32_e32 v132, v132
	v_rcp_f32_e32 v133, v133
	v_rcp_f32_e32 v136, v136
	v_rcp_f32_e32 v137, v137
	v_lshlrev_b32_e32 v134, 16, v178
	v_and_b32_e32 v135, 0xffff0000, v178
	v_lshlrev_b32_e32 v138, 16, v179
	v_and_b32_e32 v139, 0xffff0000, v179
	v_pk_mul_f32 v[132:133], v[132:133], v[134:135]
	v_pk_mul_f32 v[136:137], v[136:137], v[138:139]
	v_pk_mul_f32 v[4:5], v[4:5], v[132:133]
	v_pk_mul_f32 v[6:7], v[6:7], v[136:137]
	s_and_b64 vcc, exec, s[40:41]
	s_mov_b64 s[40:41], -1
	s_cbranch_vccnz .LBB0_604
